# speedup vs baseline: 1.0508x; 1.0017x over previous
; #define SBAR() __builtin_amdgcn_sched_barrier(0)
; #define SLOAD(i, key0) do { sr_[i].v = *reinterpret_cast<const bf16x8*>(&Vh[(long)((key0) + vr) * ldv + vc]); \
;     sr_[i].k0 = *reinterpret_cast<const bf16x8*>(&Kh[(long)((key0) + kr0) * ldk + kc0]); \
;     if (k2) sr_[i].k1 = *reinterpret_cast<const bf16x8*>(&Kh[(long)((key0) + kr1) * ldk + kc1]); } while (0)
; __device__ __forceinline__ void finishSM(f32x16& p0, f32x16& p1, float alpha, float& l_reg, bf16x8& pa0, bf16x8& pa1, bf16x8& pa2, bf16x8& pa3) {
; #pragma unroll
;   for (int r = 0; r < 16; ++r) p1[r] = __builtin_amdgcn_exp2f(p1[r]);
;   float ps = 0;
; #pragma unroll
;   for (int r = 0; r < 16; ++r) ps += p0[r];
; #pragma unroll
;   for (int r = 0; r < 16; ++r) ps += p1[r];
;   { auto rr = __builtin_amdgcn_permlane32_swap(__float_as_uint(ps), __float_as_uint(ps), false, false);
;     ps = __uint_as_float(rr[0]) + __uint_as_float(rr[1]); }
;   l_reg = l_reg * alpha + ps;
;     ...
;   PK4(p0, 0, pa0); PK4(p0, 8, pa1); PK4(p1, 0, pa2); PK4(p1, 8, pa3);
; template <int DQK, bool FIX>
; __device__ __forceinline__ void attn_item(const bf16* Qb, const bf16* __restrict__ Kh, const bf16* __restrict__ Vh,
;                                           u16* Ob, int q0, int L, int NT, char* lds, float mC) {
;     ...
;     if (act) { SBAR(); qkt<DQK>(pB0, pB1, (bf16*)((char*)K_lds + SHM_K), qr, r32, hi, j * KVBLK, L);
;       finishSM(pA0, pA1, alA, l_reg, pa0, pa1, pa2, pa3); SBAR(); }
;     SLOAD(SO, (j + 2) * KVBLK); SBAR();
;     if (act) { pv_d0(o, vb0, pa0, pa1, pa2, pa3); partialSM<DQK, FIX>(pB0, pB1, m_reg, mnB, alB, mC); }
.LBB0_832:
	s_and_saveexec_b64 s[2:3], s[8:9]
	s_cbranch_execz .LBB0_838
	s_add_i32 s6, s78, 64
	s_cmp_le_u32 s6, s79
	s_cbranch_scc0 .Lslow64a
	s_and_b64 vcc, exec, s[10:11]
	s_cbranch_vccz .Lslow64a
	ds_read_b128 v[222:225], v167 offset:49152
	ds_read_b128 v[226:229], v168 offset:49152
	ds_read_b128 v[230:233], v167 offset:57344
	ds_read_b128 v[234:237], v168 offset:57344
	ds_read_b128 v[238:241], v169 offset:49152
	ds_read_b128 v[242:245], v169 offset:57344
	ds_read_b128 v[246:249], v171 offset:49152
	ds_read_b128 v[250:253], v171 offset:57344
	v_cvt_pk_bf16_f32 v130, v50, v51
	v_cvt_pk_bf16_f32 v131, v52, v53
	v_cvt_pk_bf16_f32 v132, v54, v55
	v_cvt_pk_bf16_f32 v133, v56, v57
	v_cvt_pk_bf16_f32 v134, v58, v59
	v_cvt_pk_bf16_f32 v135, v60, v61
	v_cvt_pk_bf16_f32 v136, v62, v63
	v_cvt_pk_bf16_f32 v137, v64, v65
	s_waitcnt lgkmcnt(7)
	v_mfma_f32_32x32x16_bf16 v[66:81], v[222:225], v[98:101], 0
	ds_read_b64_tr_b16 v[186:187], v166 offset:0
	ds_read_b64_tr_b16 v[188:189], v166 offset:2048
	ds_read_b64_tr_b16 v[190:191], v166 offset:4096
	ds_read_b64_tr_b16 v[192:193], v166 offset:6144
	v_exp_f32_e32 v34, v34
	v_exp_f32_e32 v35, v35
	v_add_f32_e32 v208, 0, v50
	v_add_f32_e32 v208, v51, v208
	s_waitcnt lgkmcnt(10)
	v_mfma_f32_32x32x16_bf16 v[66:81], v[226:229], v[102:105], v[66:81]
	ds_read_b64_tr_b16 v[194:195], v166 offset:8192
	ds_read_b64_tr_b16 v[196:197], v166 offset:10240
	ds_read_b64_tr_b16 v[198:199], v166 offset:12288
	ds_read_b64_tr_b16 v[200:201], v166 offset:14336
	v_exp_f32_e32 v36, v36
	v_exp_f32_e32 v37, v37
	v_exp_f32_e32 v38, v38
	v_add_f32_e32 v208, v52, v208
	s_waitcnt lgkmcnt(13)
	v_mfma_f32_32x32x16_bf16 v[82:97], v[230:233], v[98:101], 0
	v_exp_f32_e32 v39, v39
	v_exp_f32_e32 v40, v40
	v_add_f32_e32 v208, v53, v208
	v_add_f32_e32 v208, v54, v208
	s_waitcnt lgkmcnt(12)
	v_mfma_f32_32x32x16_bf16 v[82:97], v[234:237], v[102:105], v[82:97]
	v_exp_f32_e32 v41, v41
	v_exp_f32_e32 v42, v42
	v_exp_f32_e32 v43, v43
	v_add_f32_e32 v208, v55, v208
	s_waitcnt lgkmcnt(11)
	v_mfma_f32_32x32x16_bf16 v[66:81], v[238:241], v[106:109], v[66:81]
	v_exp_f32_e32 v44, v44
	v_exp_f32_e32 v45, v45
	v_add_f32_e32 v208, v56, v208
	v_add_f32_e32 v208, v57, v208
	s_waitcnt lgkmcnt(10)
	v_mfma_f32_32x32x16_bf16 v[82:97], v[242:245], v[106:109], v[82:97]
	ds_read_b64_tr_b16 v[222:223], v166 offset:512
	ds_read_b64_tr_b16 v[224:225], v166 offset:2560
	ds_read_b64_tr_b16 v[226:227], v166 offset:4608
	ds_read_b64_tr_b16 v[228:229], v166 offset:6656
	v_exp_f32_e32 v46, v46
	v_exp_f32_e32 v47, v47
	v_exp_f32_e32 v48, v48
	v_add_f32_e32 v208, v58, v208
	s_waitcnt lgkmcnt(13)
	v_mfma_f32_32x32x16_bf16 v[66:81], v[246:249], v[110:113], v[66:81]
	v_exp_f32_e32 v49, v49
	v_cvt_pk_bf16_f32 v138, v34, v35
	v_cvt_pk_bf16_f32 v139, v36, v37
	v_cvt_pk_bf16_f32 v140, v38, v39
	v_add_f32_e32 v208, v59, v208
	s_waitcnt lgkmcnt(12)
	v_mfma_f32_32x32x16_bf16 v[82:97], v[250:253], v[110:113], v[82:97]
	ds_read_b64_tr_b16 v[230:231], v166 offset:8704
	ds_read_b64_tr_b16 v[232:233], v166 offset:10752
	ds_read_b64_tr_b16 v[234:235], v166 offset:12800
	s_waitcnt lgkmcnt(14)
	ds_read_b64_tr_b16 v[236:237], v166 offset:14848
	v_cvt_pk_bf16_f32 v141, v40, v41
	v_cvt_pk_bf16_f32 v142, v42, v43
	v_cvt_pk_bf16_f32 v143, v44, v45
	v_cvt_pk_bf16_f32 v144, v46, v47
	v_cvt_pk_bf16_f32 v145, v48, v49
	v_add_f32_e32 v208, v60, v208
	v_add_f32_e32 v208, v61, v208
	s_or_b64 exec, exec, s[2:3]
	v_lshl_add_u64 v[152:153], v[148:149], 0, s[4:5]
	v_add_co_u32_e32 v122, vcc, 0x2ced0000, v152
	v_lshl_add_u64 v[150:151], v[146:147], 0, s[4:5]
	s_nop 0
	v_addc_co_u32_e32 v123, vcc, 0, v153, vcc
	v_add_co_u32_e32 v126, vcc, 0x119d0000, v150
	global_load_dwordx4 v[122:125], v[122:123], off offset:2048
	s_nop 0
	v_addc_co_u32_e32 v127, vcc, 0, v151, vcc
	global_load_dwordx4 v[126:129], v[126:127], off
	s_and_saveexec_b64 s[2:3], s[8:9]
	s_waitcnt lgkmcnt(14)
	v_mfma_f32_32x32x16_bf16 v[2:17], v[130:133], v[186:189], v[2:17]
	v_add_f32_e32 v208, v62, v208
	v_add_f32_e32 v208, v63, v208
	v_exp_f32_e32 v66, v66
	v_exp_f32_e32 v67, v67
	s_waitcnt lgkmcnt(12)
	v_mfma_f32_32x32x16_bf16 v[2:17], v[134:137], v[190:193], v[2:17]
	v_add_f32_e32 v208, v64, v208
	v_add_f32_e32 v208, v65, v208
	v_add_f32_e32 v208, v34, v208
	v_exp_f32_e32 v68, v68
	v_exp_f32_e32 v69, v69
	s_waitcnt lgkmcnt(10)
	v_mfma_f32_32x32x16_bf16 v[2:17], v[138:141], v[194:197], v[2:17]
	v_add_f32_e32 v208, v35, v208
	v_add_f32_e32 v208, v36, v208
	v_add_f32_e32 v208, v37, v208
	v_exp_f32_e32 v70, v70
	v_exp_f32_e32 v71, v71
	s_waitcnt lgkmcnt(8)
	v_mfma_f32_32x32x16_bf16 v[2:17], v[142:145], v[198:201], v[2:17]
	v_add_f32_e32 v208, v38, v208
	v_add_f32_e32 v208, v39, v208
	v_exp_f32_e32 v72, v72
	v_exp_f32_e32 v73, v73
	s_waitcnt lgkmcnt(6)
	v_mfma_f32_32x32x16_bf16 v[18:33], v[130:133], v[222:225], v[18:33]
	v_add_f32_e32 v208, v40, v208
	v_add_f32_e32 v208, v41, v208
	v_exp_f32_e32 v74, v74
	v_exp_f32_e32 v75, v75
	s_waitcnt lgkmcnt(4)
	v_mfma_f32_32x32x16_bf16 v[18:33], v[134:137], v[226:229], v[18:33]
	v_add_f32_e32 v208, v42, v208
	v_add_f32_e32 v208, v43, v208
	v_add_f32_e32 v208, v44, v208
	v_exp_f32_e32 v76, v76
	v_exp_f32_e32 v77, v77
	s_waitcnt lgkmcnt(2)
	v_mfma_f32_32x32x16_bf16 v[18:33], v[138:141], v[230:233], v[18:33]
	v_add_f32_e32 v208, v45, v208
	v_add_f32_e32 v208, v46, v208
	v_add_f32_e32 v208, v47, v208
	v_exp_f32_e32 v78, v78
	v_exp_f32_e32 v79, v79
	s_waitcnt lgkmcnt(0)
	v_mfma_f32_32x32x16_bf16 v[18:33], v[142:145], v[234:237], v[18:33]
	v_add_f32_e32 v208, v48, v208
	v_add_f32_e32 v208, v49, v208
	v_exp_f32_e32 v80, v80
	v_exp_f32_e32 v81, v81
	v_add_f32_e32 v202, v202, v208
	s_branch .LBB0_842

; #define SBAR() __builtin_amdgcn_sched_barrier(0)
; #define SLOAD(i, key0) do { sr_[i].v = *reinterpret_cast<const bf16x8*>(&Vh[(long)((key0) + vr) * ldv + vc]); \
;     sr_[i].k0 = *reinterpret_cast<const bf16x8*>(&Kh[(long)((key0) + kr0) * ldk + kc0]); \
;     if (k2) sr_[i].k1 = *reinterpret_cast<const bf16x8*>(&Kh[(long)((key0) + kr1) * ldk + kc1]); } while (0)
; #define SWRITE(b, i) do { *(bf16x8*)((char*)V_lds + (b) * SHM_V + vst) = sr_[i].v; \
;     *(bf16x8*)((char*)K_lds + (b) * SHM_K + ksw0) = sr_[i].k0; \
;     if (k2) *(bf16x8*)((char*)K_lds + (b) * SHM_K + ksw1) = sr_[i].k1; } while (0)
; #define SWAIT() asm volatile("s_waitcnt vmcnt(2)" ::: "memory")
; #define RESC(a) do { if (__any((a) < 1.f)) { if (hi == 0) al_l[r32] = (a); asm volatile("s_waitcnt lgkmcnt(0)" ::: "memory"); \
;     _Pragma("unroll") for (int d = 0; d < 2; ++d) _Pragma("unroll") for (int r = 0; r < 16; ++r) o[d][r] *= al_l[crow(r, hi)]; } } while (0)
; __device__ __forceinline__ void finishSM(f32x16& p0, f32x16& p1, float alpha, float& l_reg, bf16x8& pa0, bf16x8& pa1, bf16x8& pa2, bf16x8& pa3) {
; #pragma unroll
;   for (int r = 0; r < 16; ++r) p1[r] = __builtin_amdgcn_exp2f(p1[r]);
;   float ps = 0;
; #pragma unroll
;   for (int r = 0; r < 16; ++r) ps += p0[r];
; #pragma unroll
;   for (int r = 0; r < 16; ++r) ps += p1[r];
;   { auto rr = __builtin_amdgcn_permlane32_swap(__float_as_uint(ps), __float_as_uint(ps), false, false);
;     ps = __uint_as_float(rr[0]) + __uint_as_float(rr[1]); }
;   l_reg = l_reg * alpha + ps;
;     ...
;   PK4(p0, 0, pa0); PK4(p0, 8, pa1); PK4(p1, 0, pa2); PK4(p1, 8, pa3);
; template <int DQK, bool FIX>
; __device__ __forceinline__ void attn_item(const bf16* Qb, const bf16* __restrict__ Kh, const bf16* __restrict__ Vh,
;                                           u16* Ob, int q0, int L, int NT, char* lds, float mC) {
;     ...
;     __syncthreads(); SWAIT(); SWRITE(0, SE);
;     if (act) { RESC(alB); } __syncthreads();
;     if (act) { SBAR(); qkt<DQK>(pA0, pA1, K_lds, qr, r32, hi, (j + 1) * KVBLK, L);
;       finishSM(pB0, pB1, alB, l_reg, pa0, pa1, pa2, pa3); SBAR(); }
;     if (j + 3 < NT) SLOAD(SE, (j + 3) * KVBLK); SBAR();
;     if (act) { pv_d0(o, vb0 + (int)SHM_V, pa0, pa1, pa2, pa3); partialSM<DQK, FIX>(pA0, pA1, m_reg, mnA, alA, mC); }
.LBB0_842:
	s_or_b64 exec, exec, s[2:3]
	s_waitcnt lgkmcnt(0)
	s_barrier
	s_waitcnt vmcnt(2)
	s_waitcnt vmcnt(2)
	ds_write_b128 v160, v[114:117]
	ds_write_b128 v161, v[118:121] offset:49152
	s_and_saveexec_b64 s[2:3], s[8:9]
	s_cbranch_execz .LBB0_848
	s_add_i32 s6, s78, 0x80
	s_cmp_le_u32 s6, s79
	s_cbranch_scc0 .Lslow64b
	s_and_b64 vcc, exec, s[10:11]
	s_cbranch_vccz .Lslow64b
	ds_read_b128 v[222:225], v167 offset:32768
	ds_read_b128 v[226:229], v168 offset:32768
	ds_read_b128 v[230:233], v167 offset:40960
	ds_read_b128 v[234:237], v168 offset:40960
	ds_read_b128 v[238:241], v169 offset:32768
	ds_read_b128 v[242:245], v169 offset:40960
	ds_read_b128 v[246:249], v171 offset:32768
	ds_read_b128 v[250:253], v171 offset:40960
	v_cvt_pk_bf16_f32 v130, v66, v67
	v_cvt_pk_bf16_f32 v131, v68, v69
	v_cvt_pk_bf16_f32 v132, v70, v71
	v_cvt_pk_bf16_f32 v133, v72, v73
	v_cvt_pk_bf16_f32 v134, v74, v75
	v_cvt_pk_bf16_f32 v135, v76, v77
	v_cvt_pk_bf16_f32 v136, v78, v79
	v_cvt_pk_bf16_f32 v137, v80, v81
	s_waitcnt lgkmcnt(7)
	v_mfma_f32_32x32x16_bf16 v[50:65], v[222:225], v[98:101], 0
	ds_read_b64_tr_b16 v[186:187], v170 offset:0
	ds_read_b64_tr_b16 v[188:189], v170 offset:2048
	ds_read_b64_tr_b16 v[190:191], v170 offset:4096
	ds_read_b64_tr_b16 v[192:193], v170 offset:6144
	v_exp_f32_e32 v82, v82
	v_exp_f32_e32 v83, v83
	v_add_f32_e32 v208, 0, v66
	v_add_f32_e32 v208, v67, v208
	s_waitcnt lgkmcnt(10)
	v_mfma_f32_32x32x16_bf16 v[50:65], v[226:229], v[102:105], v[50:65]
	ds_read_b64_tr_b16 v[194:195], v170 offset:8192
	ds_read_b64_tr_b16 v[196:197], v170 offset:10240
	ds_read_b64_tr_b16 v[198:199], v170 offset:12288
	ds_read_b64_tr_b16 v[200:201], v170 offset:14336
	v_exp_f32_e32 v84, v84
	v_exp_f32_e32 v85, v85
	v_exp_f32_e32 v86, v86
	v_add_f32_e32 v208, v68, v208
	s_waitcnt lgkmcnt(13)
	v_mfma_f32_32x32x16_bf16 v[34:49], v[230:233], v[98:101], 0
	v_exp_f32_e32 v87, v87
	v_exp_f32_e32 v88, v88
	v_add_f32_e32 v208, v69, v208
	v_add_f32_e32 v208, v70, v208
	s_waitcnt lgkmcnt(12)
	v_mfma_f32_32x32x16_bf16 v[34:49], v[234:237], v[102:105], v[34:49]
	v_exp_f32_e32 v89, v89
	v_exp_f32_e32 v90, v90
	v_exp_f32_e32 v91, v91
	v_add_f32_e32 v208, v71, v208
	s_waitcnt lgkmcnt(11)
	v_mfma_f32_32x32x16_bf16 v[50:65], v[238:241], v[106:109], v[50:65]
	v_exp_f32_e32 v92, v92
	v_exp_f32_e32 v93, v93
	v_add_f32_e32 v208, v72, v208
	v_add_f32_e32 v208, v73, v208
	s_waitcnt lgkmcnt(10)
	v_mfma_f32_32x32x16_bf16 v[34:49], v[242:245], v[106:109], v[34:49]
	ds_read_b64_tr_b16 v[222:223], v170 offset:512
	ds_read_b64_tr_b16 v[224:225], v170 offset:2560
	ds_read_b64_tr_b16 v[226:227], v170 offset:4608
	ds_read_b64_tr_b16 v[228:229], v170 offset:6656
	v_exp_f32_e32 v94, v94
	v_exp_f32_e32 v95, v95
	v_exp_f32_e32 v96, v96
	v_add_f32_e32 v208, v74, v208
	s_waitcnt lgkmcnt(13)
	v_mfma_f32_32x32x16_bf16 v[50:65], v[246:249], v[110:113], v[50:65]
	v_exp_f32_e32 v97, v97
	v_cvt_pk_bf16_f32 v138, v82, v83
	v_cvt_pk_bf16_f32 v139, v84, v85
	v_cvt_pk_bf16_f32 v140, v86, v87
	v_add_f32_e32 v208, v75, v208
	s_waitcnt lgkmcnt(12)
	v_mfma_f32_32x32x16_bf16 v[34:49], v[250:253], v[110:113], v[34:49]
	ds_read_b64_tr_b16 v[230:231], v170 offset:8704
	ds_read_b64_tr_b16 v[232:233], v170 offset:10752
	ds_read_b64_tr_b16 v[234:235], v170 offset:12800
	s_waitcnt lgkmcnt(14)
	ds_read_b64_tr_b16 v[236:237], v170 offset:14848
	v_cvt_pk_bf16_f32 v141, v88, v89
	v_cvt_pk_bf16_f32 v142, v90, v91
	v_cvt_pk_bf16_f32 v143, v92, v93
	v_cvt_pk_bf16_f32 v144, v94, v95
	v_cvt_pk_bf16_f32 v145, v96, v97
	v_add_f32_e32 v208, v76, v208
	v_add_f32_e32 v208, v77, v208
	s_or_b64 exec, exec, s[2:3]
	s_cmp_ge_u32 s73, s97
	s_cselect_b64 s[2:3], -1, 0
	s_and_b64 vcc, exec, s[2:3]
	s_cbranch_vccnz .Lfast64b_nl
	v_add_co_u32_e32 v114, vcc, 0x2ced4000, v152
	s_nop 1
	v_addc_co_u32_e32 v115, vcc, 0, v153, vcc
	v_add_co_u32_e32 v118, vcc, 0x119d4000, v150
	global_load_dwordx4 v[114:117], v[114:115], off offset:2048
	s_nop 0
	v_addc_co_u32_e32 v119, vcc, 0, v151, vcc
	global_load_dwordx4 v[118:121], v[118:119], off
.Lfast64b_nl:
	s_and_saveexec_b64 s[6:7], s[8:9]
	s_waitcnt lgkmcnt(14)
	v_mfma_f32_32x32x16_bf16 v[2:17], v[130:133], v[186:189], v[2:17]
	v_add_f32_e32 v208, v78, v208
	v_add_f32_e32 v208, v79, v208
	v_exp_f32_e32 v50, v50
	v_exp_f32_e32 v51, v51
	s_waitcnt lgkmcnt(12)
	v_mfma_f32_32x32x16_bf16 v[2:17], v[134:137], v[190:193], v[2:17]
	v_add_f32_e32 v208, v80, v208
	v_add_f32_e32 v208, v81, v208
	v_add_f32_e32 v208, v82, v208
	v_exp_f32_e32 v52, v52
	v_exp_f32_e32 v53, v53
	s_waitcnt lgkmcnt(10)
	v_mfma_f32_32x32x16_bf16 v[2:17], v[138:141], v[194:197], v[2:17]
	v_add_f32_e32 v208, v83, v208
	v_add_f32_e32 v208, v84, v208
	v_add_f32_e32 v208, v85, v208
	v_exp_f32_e32 v54, v54
	v_exp_f32_e32 v55, v55
	s_waitcnt lgkmcnt(8)
	v_mfma_f32_32x32x16_bf16 v[2:17], v[142:145], v[198:201], v[2:17]
	v_add_f32_e32 v208, v86, v208
	v_add_f32_e32 v208, v87, v208
	v_exp_f32_e32 v56, v56
	v_exp_f32_e32 v57, v57
	s_waitcnt lgkmcnt(6)
	v_mfma_f32_32x32x16_bf16 v[18:33], v[130:133], v[222:225], v[18:33]
	v_add_f32_e32 v208, v88, v208
	v_add_f32_e32 v208, v89, v208
	v_exp_f32_e32 v58, v58
	v_exp_f32_e32 v59, v59
	s_waitcnt lgkmcnt(4)
	v_mfma_f32_32x32x16_bf16 v[18:33], v[134:137], v[226:229], v[18:33]
	v_add_f32_e32 v208, v90, v208
	v_add_f32_e32 v208, v91, v208
	v_add_f32_e32 v208, v92, v208
	v_exp_f32_e32 v60, v60
	v_exp_f32_e32 v61, v61
	s_waitcnt lgkmcnt(2)
	v_mfma_f32_32x32x16_bf16 v[18:33], v[138:141], v[230:233], v[18:33]
	v_add_f32_e32 v208, v93, v208
	v_add_f32_e32 v208, v94, v208
	v_add_f32_e32 v208, v95, v208
	v_exp_f32_e32 v62, v62
	v_exp_f32_e32 v63, v63
	s_waitcnt lgkmcnt(0)
	v_mfma_f32_32x32x16_bf16 v[18:33], v[142:145], v[234:237], v[18:33]
	v_add_f32_e32 v208, v96, v208
	v_add_f32_e32 v208, v97, v208
	v_exp_f32_e32 v64, v64
	v_exp_f32_e32 v65, v65
	v_add_f32_e32 v202, v202, v208
	s_branch .LBB0_831

; #define SBAR() __builtin_amdgcn_sched_barrier(0)
; #define SLOAD(i, key0) do { sr_[i].v = *reinterpret_cast<const bf16x8*>(&Vh[(long)((key0) + vr) * ldv + vc]); \
;     sr_[i].k0 = *reinterpret_cast<const bf16x8*>(&Kh[(long)((key0) + kr0) * ldk + kc0]); \
;     if (k2) sr_[i].k1 = *reinterpret_cast<const bf16x8*>(&Kh[(long)((key0) + kr1) * ldk + kc1]); } while (0)
; __device__ __forceinline__ void finishSM(f32x16& p0, f32x16& p1, float alpha, float& l_reg, bf16x8& pa0, bf16x8& pa1, bf16x8& pa2, bf16x8& pa3) {
; #pragma unroll
;   for (int r = 0; r < 16; ++r) p1[r] = __builtin_amdgcn_exp2f(p1[r]);
;   float ps = 0;
; #pragma unroll
;   for (int r = 0; r < 16; ++r) ps += p0[r];
; #pragma unroll
;   for (int r = 0; r < 16; ++r) ps += p1[r];
;   { auto rr = __builtin_amdgcn_permlane32_swap(__float_as_uint(ps), __float_as_uint(ps), false, false);
;     ps = __uint_as_float(rr[0]) + __uint_as_float(rr[1]); }
;   l_reg = l_reg * alpha + ps;
;     ...
;   PK4(p0, 0, pa0); PK4(p0, 8, pa1); PK4(p1, 0, pa2); PK4(p1, 8, pa3);
; template <int DQK, bool FIX>
; __device__ __forceinline__ void attn_item(const bf16* Qb, const bf16* __restrict__ Kh, const bf16* __restrict__ Vh,
;                                           u16* Ob, int q0, int L, int NT, char* lds, float mC) {
;     ...
;     if (act) { SBAR(); qkt<DQK>(pB0, pB1, (bf16*)((char*)K_lds + SHM_K), qr, r32, hi, j * KVBLK, L);
;       finishSM(pA0, pA1, alA, l_reg, pa0, pa1, pa2, pa3); SBAR(); }
;     SLOAD(SO, (j + 2) * KVBLK); SBAR();
;     if (act) { pv_d0(o, vb0, pa0, pa1, pa2, pa3); partialSM<DQK, FIX>(pB0, pB1, m_reg, mnB, alB, mC); }
.LBB0_883:
	s_and_saveexec_b64 s[2:3], s[10:11]
	s_cbranch_execz .LBB0_889
	s_add_i32 s14, s4, 64
	s_cmp_le_u32 s14, s5
	s_cbranch_scc0 .Lslow96a
	s_and_b64 vcc, exec, s[12:13]
	s_cbranch_vccz .Lslow96a
	ds_read_b128 v[222:225], v200 offset:49152
	ds_read_b128 v[226:229], v200 offset:57344
	ds_read_b128 v[230:233], v201 offset:49152
	ds_read_b128 v[234:237], v201 offset:57344
	ds_read_b128 v[238:241], v202 offset:49152
	ds_read_b128 v[242:245], v202 offset:57344
	ds_read_b128 v[246:249], v203 offset:49152
	ds_read_b128 v[250:253], v203 offset:57344
	v_cvt_pk_bf16_f32 v10, v64, v65
	v_cvt_pk_bf16_f32 v11, v66, v67
	v_cvt_pk_bf16_f32 v12, v68, v69
	v_cvt_pk_bf16_f32 v13, v70, v71
	v_cvt_pk_bf16_f32 v152, v72, v73
	v_cvt_pk_bf16_f32 v153, v74, v75
	v_cvt_pk_bf16_f32 v154, v76, v77
	v_cvt_pk_bf16_f32 v155, v78, v79
	s_waitcnt lgkmcnt(7)
	v_mfma_f32_32x32x16_bf16 v[80:95], v[222:225], v[112:115], 0
	ds_read_b128 v[222:225], v204 offset:49152
	ds_read_b64_tr_b16 v[206:207], v197 offset:0
	ds_read_b64_tr_b16 v[208:209], v197 offset:2048
	ds_read_b64_tr_b16 v[210:211], v197 offset:4096
	ds_read_b64_tr_b16 v[212:213], v197 offset:6144
	v_exp_f32_e32 v48, v48
	v_exp_f32_e32 v49, v49
	v_add_f32_e32 v0, 0, v64
	s_waitcnt lgkmcnt(11)
	v_mfma_f32_32x32x16_bf16 v[96:111], v[226:229], v[112:115], 0
	ds_read_b128 v[226:229], v204 offset:57344
	ds_read_b64_tr_b16 v[214:215], v197 offset:8192
	ds_read_b64_tr_b16 v[216:217], v197 offset:10240
	ds_read_b64_tr_b16 v[218:219], v197 offset:12288
	s_waitcnt lgkmcnt(14)
	ds_read_b64_tr_b16 v[220:221], v197 offset:14336
	v_exp_f32_e32 v50, v50
	v_exp_f32_e32 v51, v51
	v_add_f32_e32 v0, v65, v0
	v_mfma_f32_32x32x16_bf16 v[80:95], v[230:233], v[116:119], v[80:95]
	s_waitcnt lgkmcnt(14)
	ds_read_b128 v[230:233], v205 offset:49152
	v_exp_f32_e32 v52, v52
	v_exp_f32_e32 v53, v53
	v_add_f32_e32 v0, v66, v0
	v_mfma_f32_32x32x16_bf16 v[96:111], v[234:237], v[116:119], v[96:111]
	s_waitcnt lgkmcnt(14)
	ds_read_b128 v[234:237], v205 offset:57344
	v_exp_f32_e32 v54, v54
	v_exp_f32_e32 v55, v55
	v_add_f32_e32 v0, v67, v0
	v_mfma_f32_32x32x16_bf16 v[80:95], v[238:241], v[120:123], v[80:95]
	v_exp_f32_e32 v56, v56
	v_exp_f32_e32 v57, v57
	v_add_f32_e32 v0, v68, v0
	s_waitcnt lgkmcnt(14)
	v_mfma_f32_32x32x16_bf16 v[96:111], v[242:245], v[120:123], v[96:111]
	v_exp_f32_e32 v58, v58
	v_exp_f32_e32 v59, v59
	v_add_f32_e32 v0, v69, v0
	s_waitcnt lgkmcnt(13)
	v_mfma_f32_32x32x16_bf16 v[80:95], v[246:249], v[124:127], v[80:95]
	v_exp_f32_e32 v60, v60
	v_exp_f32_e32 v61, v61
	v_add_f32_e32 v0, v70, v0
	s_waitcnt lgkmcnt(12)
	v_mfma_f32_32x32x16_bf16 v[96:111], v[250:253], v[124:127], v[96:111]
	v_exp_f32_e32 v62, v62
	v_exp_f32_e32 v63, v63
	v_add_f32_e32 v0, v71, v0
	s_waitcnt lgkmcnt(11)
	v_mfma_f32_32x32x16_bf16 v[80:95], v[222:225], v[128:131], v[80:95]
	ds_read_b64_tr_b16 v[238:239], v197 offset:512
	ds_read_b64_tr_b16 v[240:241], v197 offset:2560
	ds_read_b64_tr_b16 v[242:243], v197 offset:4608
	ds_read_b64_tr_b16 v[244:245], v197 offset:6656
	v_cvt_pk_bf16_f32 v156, v48, v49
	v_cvt_pk_bf16_f32 v157, v50, v51
	v_cvt_pk_bf16_f32 v158, v52, v53
	v_cvt_pk_bf16_f32 v159, v54, v55
	v_add_f32_e32 v0, v72, v0
	v_add_f32_e32 v0, v73, v0
	s_waitcnt lgkmcnt(10)
	v_mfma_f32_32x32x16_bf16 v[96:111], v[226:229], v[128:131], v[96:111]
	v_cvt_pk_bf16_f32 v160, v56, v57
	v_cvt_pk_bf16_f32 v161, v58, v59
	v_cvt_pk_bf16_f32 v162, v60, v61
	v_cvt_pk_bf16_f32 v163, v62, v63
	v_add_f32_e32 v0, v74, v0
	v_add_f32_e32 v0, v75, v0
	s_waitcnt lgkmcnt(5)
	v_mfma_f32_32x32x16_bf16 v[80:95], v[230:233], v[132:135], v[80:95]
	ds_read_b64_tr_b16 v[246:247], v197 offset:8704
	ds_read_b64_tr_b16 v[248:249], v197 offset:10752
	ds_read_b64_tr_b16 v[250:251], v197 offset:12800
	ds_read_b64_tr_b16 v[252:253], v197 offset:14848
	v_add_f32_e32 v0, v76, v0
	v_add_f32_e32 v0, v77, v0
	v_add_f32_e32 v0, v78, v0
	v_add_f32_e32 v0, v79, v0
	v_add_f32_e32 v0, v48, v0
	s_waitcnt lgkmcnt(8)
	v_mfma_f32_32x32x16_bf16 v[96:111], v[234:237], v[132:135], v[96:111]
	v_add_f32_e32 v0, v49, v0
	v_add_f32_e32 v0, v50, v0
	v_add_f32_e32 v0, v51, v0
	v_add_f32_e32 v0, v52, v0
	v_add_f32_e32 v0, v53, v0
	s_or_b64 exec, exec, s[2:3]
	v_add_co_u32_e32 v2, vcc, 0xffff0000, v170
	v_lshl_add_u64 v[14:15], v[168:169], 0, s[6:7]
	s_nop 0
	v_addc_co_u32_e32 v3, vcc, -1, v171, vcc
	v_add_co_u32_e32 v6, vcc, 0xa160000, v14
	global_load_dwordx4 v[2:5], v[2:3], off
	s_nop 0
	v_addc_co_u32_e32 v7, vcc, 0, v15, vcc
	global_load_dwordx4 v[6:9], v[6:7], off
	s_and_saveexec_b64 s[2:3], s[8:9]
	s_cbranch_execz .Lfast96a_k2
	v_lshl_add_u64 v[140:141], v[166:167], 0, s[6:7]
	v_add_co_u32_e32 v140, vcc, 0xa160000, v140
	s_nop 1
	v_addc_co_u32_e32 v141, vcc, 0, v141, vcc
	global_load_dwordx4 v[140:143], v[140:141], off
.Lfast96a_k2:
	s_or_b64 exec, exec, s[2:3]
	s_and_saveexec_b64 s[2:3], s[10:11]
	v_mfma_f32_32x32x16_bf16 v[32:47], v[10:13], v[206:209], v[32:47]
	v_add_f32_e32 v0, v54, v0
	v_exp_f32_e32 v80, v80
	v_exp_f32_e32 v81, v81
	v_mfma_f32_32x32x16_bf16 v[32:47], v[152:155], v[210:213], v[32:47]
	v_add_f32_e32 v0, v55, v0
	v_exp_f32_e32 v82, v82
	v_exp_f32_e32 v83, v83
	v_mfma_f32_32x32x16_bf16 v[32:47], v[156:159], v[214:217], v[32:47]
	v_add_f32_e32 v0, v56, v0
	v_add_f32_e32 v0, v57, v0
	v_exp_f32_e32 v84, v84
	v_exp_f32_e32 v85, v85
	v_mfma_f32_32x32x16_bf16 v[32:47], v[160:163], v[218:221], v[32:47]
	v_add_f32_e32 v0, v58, v0
	v_exp_f32_e32 v86, v86
	v_exp_f32_e32 v87, v87
	s_waitcnt lgkmcnt(6)
	v_mfma_f32_32x32x16_bf16 v[16:31], v[10:13], v[238:241], v[16:31]
	v_add_f32_e32 v0, v59, v0
	v_exp_f32_e32 v88, v88
	v_exp_f32_e32 v89, v89
	s_waitcnt lgkmcnt(4)
	v_mfma_f32_32x32x16_bf16 v[16:31], v[152:155], v[242:245], v[16:31]
	v_add_f32_e32 v0, v60, v0
	v_add_f32_e32 v0, v61, v0
	v_exp_f32_e32 v90, v90
	v_exp_f32_e32 v91, v91
	s_waitcnt lgkmcnt(2)
	v_mfma_f32_32x32x16_bf16 v[16:31], v[156:159], v[246:249], v[16:31]
	v_add_f32_e32 v0, v62, v0
	v_exp_f32_e32 v92, v92
	v_exp_f32_e32 v93, v93
	s_waitcnt lgkmcnt(0)
	v_mfma_f32_32x32x16_bf16 v[16:31], v[160:163], v[250:253], v[16:31]
	v_add_f32_e32 v0, v63, v0
	v_exp_f32_e32 v94, v94
	v_exp_f32_e32 v95, v95
	v_add_f32_e32 v186, v186, v0
	s_branch .LBB0_895

; #define SBAR() __builtin_amdgcn_sched_barrier(0)
; #define SLOAD(i, key0) do { sr_[i].v = *reinterpret_cast<const bf16x8*>(&Vh[(long)((key0) + vr) * ldv + vc]); \
;     sr_[i].k0 = *reinterpret_cast<const bf16x8*>(&Kh[(long)((key0) + kr0) * ldk + kc0]); \
;     if (k2) sr_[i].k1 = *reinterpret_cast<const bf16x8*>(&Kh[(long)((key0) + kr1) * ldk + kc1]); } while (0)
; #define SWRITE(b, i) do { *(bf16x8*)((char*)V_lds + (b) * SHM_V + vst) = sr_[i].v; \
;     *(bf16x8*)((char*)K_lds + (b) * SHM_K + ksw0) = sr_[i].k0; \
;     if (k2) *(bf16x8*)((char*)K_lds + (b) * SHM_K + ksw1) = sr_[i].k1; } while (0)
; #define SWAIT() asm volatile("s_waitcnt vmcnt(2)" ::: "memory")
; #define RESC(a) do { if (__any((a) < 1.f)) { if (hi == 0) al_l[r32] = (a); asm volatile("s_waitcnt lgkmcnt(0)" ::: "memory"); \
;     _Pragma("unroll") for (int d = 0; d < 2; ++d) _Pragma("unroll") for (int r = 0; r < 16; ++r) o[d][r] *= al_l[crow(r, hi)]; } } while (0)
; __device__ __forceinline__ void finishSM(f32x16& p0, f32x16& p1, float alpha, float& l_reg, bf16x8& pa0, bf16x8& pa1, bf16x8& pa2, bf16x8& pa3) {
; #pragma unroll
;   for (int r = 0; r < 16; ++r) p1[r] = __builtin_amdgcn_exp2f(p1[r]);
;   float ps = 0;
; #pragma unroll
;   for (int r = 0; r < 16; ++r) ps += p0[r];
; #pragma unroll
;   for (int r = 0; r < 16; ++r) ps += p1[r];
;   { auto rr = __builtin_amdgcn_permlane32_swap(__float_as_uint(ps), __float_as_uint(ps), false, false);
;     ps = __uint_as_float(rr[0]) + __uint_as_float(rr[1]); }
;   l_reg = l_reg * alpha + ps;
;     ...
;   PK4(p0, 0, pa0); PK4(p0, 8, pa1); PK4(p1, 0, pa2); PK4(p1, 8, pa3);
; template <int DQK, bool FIX>
; __device__ __forceinline__ void attn_item(const bf16* Qb, const bf16* __restrict__ Kh, const bf16* __restrict__ Vh,
;                                           u16* Ob, int q0, int L, int NT, char* lds, float mC) {
;     ...
;     __syncthreads(); SWAIT(); SWRITE(0, SE);
;     if (act) { RESC(alB); } __syncthreads();
;     if (act) { SBAR(); qkt<DQK>(pA0, pA1, K_lds, qr, r32, hi, (j + 1) * KVBLK, L);
;       finishSM(pB0, pB1, alB, l_reg, pa0, pa1, pa2, pa3); SBAR(); }
;     if (j + 3 < NT) SLOAD(SE, (j + 3) * KVBLK); SBAR();
.LBB0_895:
	s_or_b64 exec, exec, s[2:3]
	s_waitcnt lgkmcnt(0)
	s_barrier
	s_waitcnt vmcnt(2)
	s_waitcnt vmcnt(3)
	ds_write_b128 v193, v[144:147]
	s_waitcnt vmcnt(2)
	ds_write_b128 v194, v[148:151] offset:49152
	s_and_saveexec_b64 s[2:3], s[8:9]
	ds_write_b128 v195, v[136:139] offset:49152
	s_or_b64 exec, exec, s[2:3]
	s_and_saveexec_b64 s[2:3], s[10:11]
	s_cbranch_execz .LBB0_903
	s_add_i32 s14, s4, 0x80
	s_cmp_le_u32 s14, s5
	s_cbranch_scc0 .Lslow96b
	s_and_b64 vcc, exec, s[12:13]
	s_cbranch_vccz .Lslow96b
	ds_read_b128 v[222:225], v200 offset:32768
	ds_read_b128 v[226:229], v200 offset:40960
	ds_read_b128 v[230:233], v201 offset:32768
	ds_read_b128 v[234:237], v201 offset:40960
	ds_read_b128 v[238:241], v202 offset:32768
	ds_read_b128 v[242:245], v202 offset:40960
	ds_read_b128 v[246:249], v203 offset:32768
	ds_read_b128 v[250:253], v203 offset:40960
	v_cvt_pk_bf16_f32 v10, v80, v81
	v_cvt_pk_bf16_f32 v11, v82, v83
	v_cvt_pk_bf16_f32 v12, v84, v85
	v_cvt_pk_bf16_f32 v13, v86, v87
	v_cvt_pk_bf16_f32 v152, v88, v89
	v_cvt_pk_bf16_f32 v153, v90, v91
	v_cvt_pk_bf16_f32 v154, v92, v93
	v_cvt_pk_bf16_f32 v155, v94, v95
	s_waitcnt lgkmcnt(7)
	v_mfma_f32_32x32x16_bf16 v[64:79], v[222:225], v[112:115], 0
	ds_read_b128 v[222:225], v204 offset:32768
	ds_read_b64_tr_b16 v[206:207], v199 offset:0
	ds_read_b64_tr_b16 v[208:209], v199 offset:2048
	ds_read_b64_tr_b16 v[210:211], v199 offset:4096
	ds_read_b64_tr_b16 v[212:213], v199 offset:6144
	v_exp_f32_e32 v96, v96
	v_exp_f32_e32 v97, v97
	v_add_f32_e32 v0, 0, v80
	s_waitcnt lgkmcnt(11)
	v_mfma_f32_32x32x16_bf16 v[48:63], v[226:229], v[112:115], 0
	ds_read_b128 v[226:229], v204 offset:40960
	ds_read_b64_tr_b16 v[214:215], v199 offset:8192
	ds_read_b64_tr_b16 v[216:217], v199 offset:10240
	ds_read_b64_tr_b16 v[218:219], v199 offset:12288
	s_waitcnt lgkmcnt(14)
	ds_read_b64_tr_b16 v[220:221], v199 offset:14336
	v_exp_f32_e32 v98, v98
	v_exp_f32_e32 v99, v99
	v_add_f32_e32 v0, v81, v0
	v_mfma_f32_32x32x16_bf16 v[64:79], v[230:233], v[116:119], v[64:79]
	s_waitcnt lgkmcnt(14)
	ds_read_b128 v[230:233], v205 offset:32768
	v_exp_f32_e32 v100, v100
	v_exp_f32_e32 v101, v101
	v_add_f32_e32 v0, v82, v0
	v_mfma_f32_32x32x16_bf16 v[48:63], v[234:237], v[116:119], v[48:63]
	s_waitcnt lgkmcnt(14)
	ds_read_b128 v[234:237], v205 offset:40960
	v_exp_f32_e32 v102, v102
	v_exp_f32_e32 v103, v103
	v_add_f32_e32 v0, v83, v0
	v_mfma_f32_32x32x16_bf16 v[64:79], v[238:241], v[120:123], v[64:79]
	v_exp_f32_e32 v104, v104
	v_exp_f32_e32 v105, v105
	v_add_f32_e32 v0, v84, v0
	s_waitcnt lgkmcnt(14)
	v_mfma_f32_32x32x16_bf16 v[48:63], v[242:245], v[120:123], v[48:63]
	v_exp_f32_e32 v106, v106
	v_exp_f32_e32 v107, v107
	v_add_f32_e32 v0, v85, v0
	s_waitcnt lgkmcnt(13)
	v_mfma_f32_32x32x16_bf16 v[64:79], v[246:249], v[124:127], v[64:79]
	v_exp_f32_e32 v108, v108
	v_exp_f32_e32 v109, v109
	v_add_f32_e32 v0, v86, v0
	s_waitcnt lgkmcnt(12)
	v_mfma_f32_32x32x16_bf16 v[48:63], v[250:253], v[124:127], v[48:63]
	v_exp_f32_e32 v110, v110
	v_exp_f32_e32 v111, v111
	v_add_f32_e32 v0, v87, v0
	s_waitcnt lgkmcnt(11)
	v_mfma_f32_32x32x16_bf16 v[64:79], v[222:225], v[128:131], v[64:79]
	ds_read_b64_tr_b16 v[238:239], v199 offset:512
	ds_read_b64_tr_b16 v[240:241], v199 offset:2560
	ds_read_b64_tr_b16 v[242:243], v199 offset:4608
	ds_read_b64_tr_b16 v[244:245], v199 offset:6656
	v_cvt_pk_bf16_f32 v156, v96, v97
	v_cvt_pk_bf16_f32 v157, v98, v99
	v_cvt_pk_bf16_f32 v158, v100, v101
	v_cvt_pk_bf16_f32 v159, v102, v103
	v_add_f32_e32 v0, v88, v0
	v_add_f32_e32 v0, v89, v0
	s_waitcnt lgkmcnt(10)
	v_mfma_f32_32x32x16_bf16 v[48:63], v[226:229], v[128:131], v[48:63]
	v_cvt_pk_bf16_f32 v160, v104, v105
	v_cvt_pk_bf16_f32 v161, v106, v107
	v_cvt_pk_bf16_f32 v162, v108, v109
	v_cvt_pk_bf16_f32 v163, v110, v111
	v_add_f32_e32 v0, v90, v0
	v_add_f32_e32 v0, v91, v0
	s_waitcnt lgkmcnt(5)
	v_mfma_f32_32x32x16_bf16 v[64:79], v[230:233], v[132:135], v[64:79]
	ds_read_b64_tr_b16 v[246:247], v199 offset:8704
	ds_read_b64_tr_b16 v[248:249], v199 offset:10752
	ds_read_b64_tr_b16 v[250:251], v199 offset:12800
	ds_read_b64_tr_b16 v[252:253], v199 offset:14848
	v_add_f32_e32 v0, v92, v0
	v_add_f32_e32 v0, v93, v0
	v_add_f32_e32 v0, v94, v0
	v_add_f32_e32 v0, v95, v0
	v_add_f32_e32 v0, v96, v0
	s_waitcnt lgkmcnt(8)
	v_mfma_f32_32x32x16_bf16 v[48:63], v[234:237], v[132:135], v[48:63]
	v_add_f32_e32 v0, v97, v0
	v_add_f32_e32 v0, v98, v0
	v_add_f32_e32 v0, v99, v0
	v_add_f32_e32 v0, v100, v0
	v_add_f32_e32 v0, v101, v0
	s_or_b64 exec, exec, s[2:3]
	s_cmp_ge_u32 s79, s97
	s_cselect_b64 s[2:3], -1, 0
	s_and_b64 vcc, exec, s[2:3]
	s_cbranch_vccnz .Lfast96b_nl
	v_add_co_u32_e32 v14, vcc, 0xa178000, v14
	global_load_dwordx4 v[144:147], v[170:171], off
	s_nop 0
	v_addc_co_u32_e32 v15, vcc, 0, v15, vcc
	global_load_dwordx4 v[148:151], v[14:15], off
	s_and_saveexec_b64 s[14:15], s[8:9]
	s_cbranch_execz .Lfast96b_k2
	v_lshl_add_u64 v[14:15], v[166:167], 0, s[6:7]
	v_add_co_u32_e32 v14, vcc, 0xa178000, v14
	s_nop 1
	v_addc_co_u32_e32 v15, vcc, 0, v15, vcc
	global_load_dwordx4 v[136:139], v[14:15], off

; #define SBAR() __builtin_amdgcn_sched_barrier(0)
; #define SLOAD(i, key0) do { sr_[i].v = *reinterpret_cast<const bf16x8*>(&Vh[(long)((key0) + vr) * ldv + vc]); \
;     sr_[i].k0 = *reinterpret_cast<const bf16x8*>(&Kh[(long)((key0) + kr0) * ldk + kc0]); \
;     if (k2) sr_[i].k1 = *reinterpret_cast<const bf16x8*>(&Kh[(long)((key0) + kr1) * ldk + kc1]); } while (0)
; template <int D0> __device__ __forceinline__ void pv_one(f32x16& od, int vb, bf16x8 pa0, bf16x8 pa1, bf16x8 pa2, bf16x8 pa3) {
;   const s16x4 l0 = tr_read<v_rd_off(D0, 0, 0)>(vb), h0 = tr_read<v_rd_off(D0, 0, 1)>(vb), l1 = tr_read<v_rd_off(D0, 1, 0)>(vb), h1 = tr_read<v_rd_off(D0, 1, 1)>(vb);
;   const s16x4 l2 = tr_read<v_rd_off(D0, 2, 0)>(vb), h2 = tr_read<v_rd_off(D0, 2, 1)>(vb), l3 = tr_read<v_rd_off(D0, 3, 0)>(vb), h3 = tr_read<v_rd_off(D0, 3, 1)>(vb);
;   asm volatile("s_waitcnt lgkmcnt(0)" ::: "memory"); SBAR();
;     ...
;   od = __builtin_amdgcn_mfma_f32_32x32x16_bf16(pa0, PK(l0, h0), od, 0, 0, 0);
;   od = __builtin_amdgcn_mfma_f32_32x32x16_bf16(pa1, PK(l1, h1), od, 0, 0, 0);
;   od = __builtin_amdgcn_mfma_f32_32x32x16_bf16(pa2, PK(l2, h2), od, 0, 0, 0);
;   od = __builtin_amdgcn_mfma_f32_32x32x16_bf16(pa3, PK(l3, h3), od, 0, 0, 0);
;     ...
; }
; __device__ __forceinline__ void pv_d0(f32x16* o, int vb, bf16x8 pa0, bf16x8 pa1, bf16x8 pa2, bf16x8 pa3) {
;   pv_one<0>(o[0], vb, pa0, pa1, pa2, pa3); pv_one<1>(o[1], vb, pa0, pa1, pa2, pa3);
; template <int DQK, bool FIX>
; __device__ __forceinline__ void attn_item(const bf16* Qb, const bf16* __restrict__ Kh, const bf16* __restrict__ Vh,
;                                           u16* Ob, int q0, int L, int NT, char* lds, float mC) {
;     ...
;     if (j + 3 < NT) SLOAD(SE, (j + 3) * KVBLK); SBAR();
;     if (act) { pv_d0(o, vb0 + (int)SHM_V, pa0, pa1, pa2, pa3); partialSM<DQK, FIX>(pA0, pA1, m_reg, mnA, alA, mC); }
.Lfast96b_nl:
	s_and_saveexec_b64 s[14:15], s[10:11]
	v_mfma_f32_32x32x16_bf16 v[32:47], v[10:13], v[206:209], v[32:47]
	v_add_f32_e32 v0, v102, v0
	v_exp_f32_e32 v64, v64
	v_exp_f32_e32 v65, v65
	v_mfma_f32_32x32x16_bf16 v[32:47], v[152:155], v[210:213], v[32:47]
	v_add_f32_e32 v0, v103, v0
	v_exp_f32_e32 v66, v66
	v_exp_f32_e32 v67, v67
	v_mfma_f32_32x32x16_bf16 v[32:47], v[156:159], v[214:217], v[32:47]
	v_add_f32_e32 v0, v104, v0
	v_add_f32_e32 v0, v105, v0
	v_exp_f32_e32 v68, v68
	v_exp_f32_e32 v69, v69
	v_mfma_f32_32x32x16_bf16 v[32:47], v[160:163], v[218:221], v[32:47]
	v_add_f32_e32 v0, v106, v0
	v_exp_f32_e32 v70, v70
	v_exp_f32_e32 v71, v71
	s_waitcnt lgkmcnt(6)
	v_mfma_f32_32x32x16_bf16 v[16:31], v[10:13], v[238:241], v[16:31]
	v_add_f32_e32 v0, v107, v0
	v_exp_f32_e32 v72, v72
	v_exp_f32_e32 v73, v73
	s_waitcnt lgkmcnt(4)
	v_mfma_f32_32x32x16_bf16 v[16:31], v[152:155], v[242:245], v[16:31]
	v_add_f32_e32 v0, v108, v0
	v_add_f32_e32 v0, v109, v0
	v_exp_f32_e32 v74, v74
	v_exp_f32_e32 v75, v75
	s_waitcnt lgkmcnt(2)
	v_mfma_f32_32x32x16_bf16 v[16:31], v[156:159], v[246:249], v[16:31]
	v_add_f32_e32 v0, v110, v0
	v_exp_f32_e32 v76, v76
	v_exp_f32_e32 v77, v77
	s_waitcnt lgkmcnt(0)
	v_mfma_f32_32x32x16_bf16 v[16:31], v[160:163], v[250:253], v[16:31]
	v_add_f32_e32 v0, v111, v0
	v_exp_f32_e32 v78, v78
	v_exp_f32_e32 v79, v79
	v_add_f32_e32 v186, v186, v0
	s_branch .LBB0_911
